# attention loop with seamless tile transition (sync before last 3 MFMAs, next-tile K prefetch) + P6 saddr + a_ready loads moved to epilogue start (P1,P6)
# baseline (speedup 1.0000x reference)
; #define ATT_WAIT_V(n) asm volatile("s_waitcnt vmcnt(" #n ")" ::: "memory")
; __device__ __forceinline__ void attn_block(LAS unsigned char* lds, const Ptrs& P, int b, int h, int qb, float negMb, float lam, int tid, int wid, int lane) {
;     const int comp = wid & 1, quarter = wid >> 1, l31 = lane & 31, hh = lane >> 5;
;     const int NT = 2 * qb + 2;
;     const size_t tok0 = (size_t)b * SEQ;
;     const int qpos = qb * 128 + quarter * 32 + l31;
;     bf16x8 qf[8];
;     { const bf16* qp = P.Q + (tok0 + qpos) * 1024 + h * 256 + comp * 128 + hh * 8;
; #pragma unroll
;       for (int ks = 0; ks < 8; ++ks) qf[ks] = *(const bf16x8*)(qp + ks * 16); }
;     const unsigned ldsw = (unsigned)wid * 4096u;
;     const unsigned lds0 = (unsigned)__builtin_amdgcn_readfirstlane((int)(unsigned)(uintptr_t)lds);
;     unsigned kb0, kx16, vb0, vy16;
;     { int ln_ = lane; asm volatile("" : "+v"(ln_));
;       kb0 = (unsigned)(((16 * (wid & 3) + (ln_ >> 4)) * 1024 + h * 256 + (wid >> 2) * 128) * 2); kx16 = (unsigned)(((ln_ & 15) ^ (ln_ >> 4)) << 4);
;       vb0 = (unsigned)(((h * 256 + 32 * wid + (ln_ >> 3)) * M_TOK) * 2); vy16 = (unsigned)(((ln_ & 7) ^ (ln_ >> 4)) << 4);
;       asm volatile("" : "+v"(kb0), "+v"(kx16), "+v"(vb0), "+v"(vy16)); }
;     ...
;     f32x16 o[8];
; #pragma unroll
;     for (int e = 0; e < 8; ++e)
; #pragma unroll
;         for (int r = 0; r < 16; ++r) o[e][r] = 0.f;
;     float lsum = 0.f;
;     ATT_WAIT_V(0);
; #pragma unroll
;     for (int ks = 0; ks < 8; ++ks) asm volatile("" : "+v"(qf[ks]));
;     ATT_DMA(0, 0);
.LBB0_413:
	s_xor_b64 s[40:41], s[0:1], -1
	s_and_b64 s[0:1], s[0:1], exec
	s_cselect_b32 s2, s78, s77
	s_lshl_b32 s80, s2, 7
	s_add_i32 s80, s80, s50
	v_or_b32_e32 v194, s80, v203
	v_lshl_add_u64 v[18:19], s[20:21], 0, v[194:195]
	v_lshlrev_b64 v[18:19], 11, v[18:19]
	v_lshl_add_u64 v[18:19], v[198:199], 0, v[18:19]
	flat_load_dwordx4 v[190:193], v[18:19]
	flat_load_dwordx4 v[186:189], v[18:19] offset:32
	flat_load_dwordx4 v[182:185], v[18:19] offset:64
	flat_load_dwordx4 v[178:181], v[18:19] offset:96
	flat_load_dwordx4 v[174:177], v[18:19] offset:128
	flat_load_dwordx4 v[166:169], v[18:19] offset:160
	flat_load_dwordx4 v[170:173], v[18:19] offset:192
	flat_load_dwordx4 v[162:165], v[18:19] offset:224
	v_mov_b32_e32 v51, v1
	s_lshl_b32 s82, s2, 17
	v_ashrrev_i32_e32 v52, 4, v51
	v_lshrrev_b32_e32 v53, 3, v51
	v_add_u32_e32 v54, s51, v52
	v_bitop3_b32 v55, v51, v52, 15 bitop3:0x6c
	v_bitop3_b32 v51, v51, v52, 7 bitop3:0x6c
	v_add_lshl_u32 v53, s79, v53, 16
	v_lshl_add_u32 v52, v54, 11, s4
	v_lshlrev_b32_e32 v54, 4, v55
	v_lshlrev_b32_e32 v51, 4, v51
	s_waitcnt vmcnt(0)
	v_mov_b32_e32 v194, 0
	v_add_u32_e32 v206, v52, v54
	v_xor_b32_e32 v55, 64, v54
	v_xor_b32_e32 v56, 0x80, v54
	v_add3_u32 v208, v52, v55, s71
	v_xor_b32_e32 v54, 0xc0, v54
	v_add3_u32 v209, v52, v56, s72
	v_add3_u32 v210, v52, v54, s73
	v_add_u32_e32 v207, v53, v51
	v_xad_u32 v51, v51, 64, v53
	v_add_u32_e32 v211, 0x80000, v51
	v_add_u32_e32 v212, 0x100000, v207
	v_add_u32_e32 v213, 0x180000, v51
	s_mov_b32 s81, 0
	s_mov_b64 s[0:1], s[38:39]
	s_mov_b64 s[42:43], s[36:37]
	v_mov_b32_e32 v18, 0
	v_mov_b32_e32 v34, 0
	v_mov_b32_e32 v50, 0
	v_mov_b32_e32 v19, v194
	v_mov_b32_e32 v20, v194
	v_mov_b32_e32 v21, v194
	v_mov_b32_e32 v22, v194
	v_mov_b32_e32 v23, v194
	v_mov_b32_e32 v24, v194
	v_mov_b32_e32 v25, v194
	v_mov_b32_e32 v26, v194
	v_mov_b32_e32 v27, v194
	v_mov_b32_e32 v28, v194
	v_mov_b32_e32 v29, v194
	v_mov_b32_e32 v30, v194
	v_mov_b32_e32 v31, v194
	v_mov_b32_e32 v32, v194
	v_mov_b32_e32 v33, v194
	v_mov_b32_e32 v35, v194
	v_mov_b32_e32 v36, v194
	v_mov_b32_e32 v37, v194
	v_mov_b32_e32 v38, v194
	v_mov_b32_e32 v39, v194
	v_mov_b32_e32 v40, v194
	v_mov_b32_e32 v41, v194
	v_mov_b32_e32 v42, v194
	v_mov_b32_e32 v43, v194
	v_mov_b32_e32 v44, v194
	v_mov_b32_e32 v45, v194
	v_mov_b32_e32 v46, v194
	v_mov_b32_e32 v47, v194
	v_mov_b32_e32 v48, v194
	v_mov_b32_e32 v49, v194
	s_bitset1_b32 s82, 16
	v_mov_b32_e32 v51, v194
	v_mov_b32_e32 v52, v194
	v_mov_b32_e32 v53, v194
	v_mov_b32_e32 v54, v194
	v_mov_b32_e32 v55, v194
	v_mov_b32_e32 v56, v194
	v_mov_b32_e32 v57, v194
	v_mov_b32_e32 v58, v194
	s_waitcnt vmcnt(0) lgkmcnt(0)
	s_mov_b32 s2, m0
	s_mov_b32 m0, s54
	s_nop 0
	global_load_lds_dwordx4 v206, s[24:25]
	s_mov_b32 m0, s2
	v_mov_b32_e32 v59, v194
	s_mov_b32 s2, m0
	s_mov_b32 m0, s55
	s_nop 0
	global_load_lds_dwordx4 v208, s[24:25]
	s_mov_b32 m0, s2
	v_mov_b32_e32 v60, v194
	s_mov_b32 s2, m0
	s_mov_b32 m0, s56
	s_nop 0
	global_load_lds_dwordx4 v209, s[24:25]
	s_mov_b32 m0, s2
	v_mov_b32_e32 v61, v194
	s_mov_b32 s2, m0
	s_mov_b32 m0, s57
	s_nop 0
	global_load_lds_dwordx4 v210, s[24:25]
	s_mov_b32 m0, s2
	v_mov_b32_e32 v62, v194
	s_mov_b32 s2, m0
	s_mov_b32 m0, s61
	s_nop 0
	global_load_lds_dwordx4 v207, s[26:27]
	s_mov_b32 m0, s2
	v_mov_b32_e32 v63, v194
	s_mov_b32 s2, m0
	s_mov_b32 m0, s62
	s_nop 0
	global_load_lds_dwordx4 v211, s[26:27]
	s_mov_b32 m0, s2
	v_mov_b32_e32 v64, v194
	s_mov_b32 s2, m0
	s_mov_b32 m0, s63
	s_nop 0
	global_load_lds_dwordx4 v212, s[26:27]
	s_mov_b32 m0, s2
	v_mov_b32_e32 v65, v194
	s_mov_b32 s2, m0
	s_mov_b32 m0, s64
	s_nop 0
	global_load_lds_dwordx4 v213, s[26:27]
	s_mov_b32 m0, s2
	v_mov_b32_e32 v66, 0
	v_mov_b32_e32 v67, v194
	v_mov_b32_e32 v68, v194
	v_mov_b32_e32 v69, v194
	v_mov_b32_e32 v70, v194
	v_mov_b32_e32 v71, v194
	v_mov_b32_e32 v72, v194
	v_mov_b32_e32 v73, v194
	v_mov_b32_e32 v74, v194
	v_mov_b32_e32 v75, v194
	v_mov_b32_e32 v76, v194
	v_mov_b32_e32 v77, v194
	v_mov_b32_e32 v78, v194
	v_mov_b32_e32 v79, v194
	v_mov_b32_e32 v80, v194
	v_mov_b32_e32 v81, v194
	v_mov_b32_e32 v82, 0
	v_mov_b32_e32 v83, v194
	v_mov_b32_e32 v84, v194
	v_mov_b32_e32 v85, v194
	v_mov_b32_e32 v86, v194
	v_mov_b32_e32 v87, v194
	v_mov_b32_e32 v88, v194
	v_mov_b32_e32 v89, v194
	v_mov_b32_e32 v90, v194
	v_mov_b32_e32 v91, v194
	v_mov_b32_e32 v92, v194
	v_mov_b32_e32 v93, v194
	v_mov_b32_e32 v94, v194
	v_mov_b32_e32 v95, v194
	v_mov_b32_e32 v96, v194
	v_mov_b32_e32 v97, v194
	v_mov_b32_e32 v98, 0
	v_mov_b32_e32 v99, v194
	v_mov_b32_e32 v100, v194
	v_mov_b32_e32 v101, v194
	v_mov_b32_e32 v102, v194
	v_mov_b32_e32 v103, v194
	v_mov_b32_e32 v104, v194
	v_mov_b32_e32 v105, v194
	v_mov_b32_e32 v106, v194
	v_mov_b32_e32 v107, v194
	v_mov_b32_e32 v108, v194
	v_mov_b32_e32 v109, v194
	v_mov_b32_e32 v110, v194
	v_mov_b32_e32 v111, v194
	v_mov_b32_e32 v112, v194
	v_mov_b32_e32 v113, v194
	v_mov_b32_e32 v114, 0
	v_mov_b32_e32 v115, v194
	v_mov_b32_e32 v116, v194
	v_mov_b32_e32 v117, v194
	v_mov_b32_e32 v118, v194
	v_mov_b32_e32 v119, v194
	v_mov_b32_e32 v120, v194
	v_mov_b32_e32 v121, v194
	v_mov_b32_e32 v122, v194
	v_mov_b32_e32 v123, v194
	v_mov_b32_e32 v124, v194
	v_mov_b32_e32 v125, v194
	v_mov_b32_e32 v126, v194
	v_mov_b32_e32 v127, v194
	v_mov_b32_e32 v128, v194
	v_mov_b32_e32 v129, v194
	v_mov_b32_e32 v130, 0
	v_mov_b32_e32 v131, v194
	v_mov_b32_e32 v132, v194
	v_mov_b32_e32 v133, v194
	v_mov_b32_e32 v134, v194
	v_mov_b32_e32 v135, v194
	v_mov_b32_e32 v136, v194
	v_mov_b32_e32 v137, v194
	v_mov_b32_e32 v138, v194
	v_mov_b32_e32 v139, v194
	v_mov_b32_e32 v140, v194
	v_mov_b32_e32 v141, v194
	v_mov_b32_e32 v142, v194
	v_mov_b32_e32 v143, v194
	v_mov_b32_e32 v144, v194
; #define LAS __attribute__((address_space(3)))
; #define LDS_WAIT() asm volatile("s_waitcnt lgkmcnt(0)" ::: "memory")
; __device__ __forceinline__ int pi32(int i) { return (i & ~12) | ((i & 4) << 1) | ((i & 8) >> 1); }
; #define ATT_WAIT_V(n) asm volatile("s_waitcnt vmcnt(" #n ")" ::: "memory")
; #define ATT_BAR() do { asm volatile("" ::: "memory"); __builtin_amdgcn_s_barrier(); asm volatile("" ::: "memory"); } while (0)
; __device__ __forceinline__ void attn_block(LAS unsigned char* lds, const Ptrs& P, int b, int h, int qb, float negMb, float lam, int tid, int wid, int lane) {
;     ...
;     for (int t = 0; t < NT; ++t) {
;         ATT_WAIT_V(0);
;         LDS_WAIT();
;         ATT_BAR();
;         const bool more = t + 1 < NT;
;         if (more && early) ATT_DMA(t + 1, (t + 1) & 1);
;         const bool active = (quarter >= 2) || more;
;         const LAS unsigned char* base = lds + (t & 1) * BUF;
;         int ln2 = lane; asm volatile("" : "+v"(ln2));
;         const int l31b = ln2 & 31, hhb = ln2 >> 5;
;         const int krow = pi32(l31b), kx = krow & 15;
;         const int koffr = comp * 16384 + krow * 256;
;         const int vx = (l31b >> 1) & 7;
;         const int voffr = V_OFF + l31b * 128;
; #pragma unroll
;         for (int T = 0; T < 2; ++T) {
;             if (T == 1 && more && !early) ATT_DMA(t + 1, (t + 1) & 1);
;             if (active) {
;                 f32x16 s;
; #pragma unroll
;                 for (int r = 0; r < 16; ++r) s[r] = negMb;
; #pragma unroll
;                 for (int ks = 0; ks < 8; ++ks) {
;                     const bf16x8 kf = *(const LAS bf16x8*)(base + koffr + T * 8192 + (((2 * ks + hhb) ^ kx) << 4));
;                     s = __builtin_amdgcn_mfma_f32_32x32x16_bf16(kf, qf[ks], s, 0, 0, 0);
;                 }
;                 float ps = 0.f;
; #pragma unroll
;                 for (int r = 0; r < 16; ++r) { s[r] = __builtin_amdgcn_exp2f(s[r]); ps += s[r]; }
	v_mov_b32_e32 v145, v194
	v_lshrrev_b32_e32 v226, 5, v1
	v_and_b32_e32 v227, 19, v1
	v_lshlrev_b32_e32 v228, 1, v1
	v_and_b32_e32 v228, 8, v228
	v_lshrrev_b32_e32 v229, 1, v1
	v_and_b32_e32 v230, 4, v229
	v_or3_b32 v227, v227, v228, v230
	v_and_b32_e32 v231, 15, v227
	v_lshl_add_u32 v232, v227, 8, s65
	v_xor_b32_e32 v233, v226, v231
	v_lshl_add_u32 v214, v233, 4, v232
	v_add_u32_e32 v233, 2, v226
	v_xor_b32_e32 v233, v233, v231
	v_lshl_add_u32 v215, v233, 4, v232
	v_add_u32_e32 v233, 4, v226
	v_xor_b32_e32 v233, v233, v231
	v_lshl_add_u32 v216, v233, 4, v232
	v_add_u32_e32 v233, 6, v226
	v_xor_b32_e32 v233, v233, v231
	v_lshl_add_u32 v217, v233, 4, v232
	v_add_u32_e32 v233, 8, v226
	v_xor_b32_e32 v233, v233, v231
	v_lshl_add_u32 v218, v233, 4, v232
	v_add_u32_e32 v233, 10, v226
	v_xor_b32_e32 v233, v233, v231
	v_lshl_add_u32 v219, v233, 4, v232
	v_add_u32_e32 v233, 12, v226
	v_xor_b32_e32 v233, v233, v231
	v_lshl_add_u32 v220, v233, 4, v232
	v_add_u32_e32 v233, 14, v226
	v_xor_b32_e32 v233, v233, v231
	v_lshl_add_u32 v221, v233, 4, v232
	v_and_b32_e32 v234, 7, v229
	v_and_b32_e32 v235, 31, v1
	v_lshlrev_b32_e32 v235, 7, v235
	v_xor_b32_e32 v233, v226, v234
	v_lshl_add_u32 v222, v233, 4, v235
	v_add_u32_e32 v233, 2, v226
	v_xor_b32_e32 v233, v233, v234
	v_lshl_add_u32 v223, v233, 4, v235
	v_add_u32_e32 v233, 4, v226
	v_xor_b32_e32 v233, v233, v234
	v_lshl_add_u32 v224, v233, 4, v235
	v_add_u32_e32 v233, 6, v226
	v_xor_b32_e32 v233, v233, v234
	v_lshl_add_u32 v225, v233, 4, v235
	v_mov_b32_e32 v254, 0
	v_mov_b32_e32 v255, 0
	s_waitcnt vmcnt(0)
	s_waitcnt lgkmcnt(0)
	s_barrier
	ds_read_b128 v[226:229], v214
	ds_read_b128 v[230:233], v215
	ds_read_b128 v[234:237], v216
.Lat_tile:
	s_add_i32 s44, s81, 0x10000
	s_and_b32 s83, s44, 0x10000
	s_add_i32 s84, s83, s54
	s_add_i32 s85, s83, s61
	s_and_b64 vcc, exec, s[12:13]
	s_cbranch_vccnz .Lat_qk
	s_mov_b32 s44, m0
	s_mov_b32 m0, s84
	s_nop 0
	global_load_lds_dwordx4 v206, s[0:1]
	s_mov_b32 m0, s44
	s_add_i32 s44, s84, 0x400
	s_mov_b32 s45, m0
	s_mov_b32 m0, s44
	s_nop 0
	global_load_lds_dwordx4 v208, s[0:1]
	s_mov_b32 m0, s45
	s_add_i32 s44, s84, 0x800
	s_mov_b32 s45, m0
	s_mov_b32 m0, s44
	s_nop 0
	global_load_lds_dwordx4 v209, s[0:1]
	s_mov_b32 m0, s45
	s_add_i32 s44, s84, 0xc00
	s_mov_b32 s45, m0
	s_mov_b32 m0, s44
	s_nop 0
	global_load_lds_dwordx4 v210, s[0:1]
	s_mov_b32 m0, s45
	s_mov_b32 s44, m0
	s_mov_b32 m0, s85
	s_nop 0
	global_load_lds_dwordx4 v207, s[42:43]
	s_mov_b32 m0, s44
	s_add_i32 s44, s85, 0x400
	s_mov_b32 s45, m0
	s_mov_b32 m0, s44
	s_nop 0
	global_load_lds_dwordx4 v211, s[42:43]
	s_mov_b32 m0, s45
	s_add_i32 s44, s85, 0x800
	s_mov_b32 s45, m0
	s_mov_b32 m0, s44
	s_nop 0
	global_load_lds_dwordx4 v212, s[42:43]
	s_mov_b32 m0, s45
	s_add_i32 s44, s85, 0xc00
	s_mov_b32 s45, m0
	s_mov_b32 m0, s44
	s_nop 0
	global_load_lds_dwordx4 v213, s[42:43]
	s_mov_b32 m0, s45
.Lat_qk:
	s_waitcnt lgkmcnt(2)
	v_mfma_f32_32x32x16_bf16 v[146:161], v[226:229], v[190:193], v[2:17]
	ds_read_b128 v[226:229], v217
	s_waitcnt lgkmcnt(2)
	v_mfma_f32_32x32x16_bf16 v[146:161], v[230:233], v[186:189], v[146:161]
	ds_read_b128 v[230:233], v218
	s_waitcnt lgkmcnt(2)
	v_mfma_f32_32x32x16_bf16 v[146:161], v[234:237], v[182:185], v[146:161]
	ds_read_b128 v[234:237], v219
	s_waitcnt lgkmcnt(2)
	v_mfma_f32_32x32x16_bf16 v[146:161], v[226:229], v[178:181], v[146:161]
	ds_read_b128 v[226:229], v220
	s_waitcnt lgkmcnt(2)
	v_mfma_f32_32x32x16_bf16 v[146:161], v[230:233], v[174:177], v[146:161]
	ds_read_b128 v[230:233], v221
	s_waitcnt lgkmcnt(2)
	v_mfma_f32_32x32x16_bf16 v[146:161], v[234:237], v[166:169], v[146:161]
	ds_read_b128 v[234:237], v214 offset:8192
	s_waitcnt lgkmcnt(2)
	v_mfma_f32_32x32x16_bf16 v[146:161], v[226:229], v[170:173], v[146:161]
	ds_read_b128 v[226:229], v215 offset:8192
	s_waitcnt lgkmcnt(2)
	v_mfma_f32_32x32x16_bf16 v[146:161], v[230:233], v[162:165], v[146:161]
	ds_read_b128 v[230:233], v216 offset:8192
	s_waitcnt lgkmcnt(2)
	v_mfma_f32_32x32x16_bf16 v[238:253], v[234:237], v[190:193], v[2:17]
	ds_read_b128 v[234:237], v217 offset:8192
	s_waitcnt lgkmcnt(2)
	v_mfma_f32_32x32x16_bf16 v[238:253], v[226:229], v[186:189], v[238:253]
	ds_read_b128 v[226:229], v218 offset:8192
	s_waitcnt lgkmcnt(2)
	v_mfma_f32_32x32x16_bf16 v[238:253], v[230:233], v[182:185], v[238:253]
	ds_read_b128 v[230:233], v219 offset:8192
	s_waitcnt lgkmcnt(2)
	v_mfma_f32_32x32x16_bf16 v[238:253], v[234:237], v[178:181], v[238:253]
	ds_read_b128 v[234:237], v220 offset:8192
	v_exp_f32_e32 v146, v146
	v_exp_f32_e32 v147, v147
	v_exp_f32_e32 v148, v148
	s_waitcnt lgkmcnt(2)
	v_mfma_f32_32x32x16_bf16 v[238:253], v[226:229], v[174:177], v[238:253]
	v_exp_f32_e32 v149, v149
	v_exp_f32_e32 v150, v150
	v_exp_f32_e32 v151, v151
	ds_read_b128 v[226:229], v221 offset:8192
	s_waitcnt lgkmcnt(2)
	v_mfma_f32_32x32x16_bf16 v[238:253], v[230:233], v[166:169], v[238:253]
	v_exp_f32_e32 v152, v152
	v_exp_f32_e32 v153, v153
	v_add_f32_e32 v254, v254, v146
	v_add_f32_e32 v255, v255, v147
	ds_read_b128 v[230:233], v222 offset:32768
	s_waitcnt lgkmcnt(2)
	v_mfma_f32_32x32x16_bf16 v[238:253], v[234:237], v[170:173], v[238:253]
	v_add_f32_e32 v254, v254, v148
	v_add_f32_e32 v255, v255, v149
	v_add_f32_e32 v254, v254, v150
	v_add_f32_e32 v255, v255, v151
	v_add_f32_e32 v254, v254, v152
	ds_read_b128 v[234:237], v222 offset:36864
	s_waitcnt lgkmcnt(2)
	v_mfma_f32_32x32x16_bf16 v[238:253], v[226:229], v[162:165], v[238:253]
	v_add_f32_e32 v255, v255, v153
	v_cvt_pk_bf16_f32 v146, v146, v147
	v_cvt_pk_bf16_f32 v147, v148, v149
	v_cvt_pk_bf16_f32 v148, v150, v151
	v_cvt_pk_bf16_f32 v149, v152, v153
	ds_read_b128 v[226:229], v222 offset:40960
	s_waitcnt lgkmcnt(2)
; #define LAS __attribute__((address_space(3)))
; __device__ __forceinline__ unsigned pk2(float lo, float hi) { return pg8::cvt_pk_bf16(lo, hi); }
; __device__ __forceinline__ void attn_block(LAS unsigned char* lds, const Ptrs& P, int b, int h, int qb, float negMb, float lam, int tid, int wid, int lane) {
;     ...
;                 float ps = 0.f;
; #pragma unroll
;                 for (int r = 0; r < 16; ++r) { s[r] = __builtin_amdgcn_exp2f(s[r]); ps += s[r]; }
;                 lsum += ps;
; #pragma unroll
;                 for (int sI = 0; sI < 2; ++sI) { v4u w;
; #pragma unroll
;                     for (int j = 0; j < 4; ++j) w[j] = pk2(s[8 * sI + 2 * j], s[8 * sI + 2 * j + 1]);
;                     const bf16x8 pf = __builtin_bit_cast(bf16x8, w);
;                     const LAS unsigned char* vb = base + voffr + (((2 * (2 * T + sI) + hhb) ^ vx) << 4);
; #pragma unroll
;                     for (int e = 0; e < 8; ++e) {
;                         const bf16x8 vf = *(const LAS bf16x8*)(vb + e * 4096);
;                         o[e] = __builtin_amdgcn_mfma_f32_32x32x16_bf16(vf, pf, o[e], 0, 0, 0);
;                     }
;                 }
	v_mfma_f32_32x32x16_bf16 v[130:145], v[230:233], v[146:149], v[130:145]
	v_exp_f32_e32 v154, v154
	v_exp_f32_e32 v155, v155
	v_exp_f32_e32 v156, v156
	ds_read_b128 v[230:233], v222 offset:45056
	s_waitcnt lgkmcnt(2)
	v_mfma_f32_32x32x16_bf16 v[114:129], v[234:237], v[146:149], v[114:129]
	v_exp_f32_e32 v157, v157
	v_exp_f32_e32 v158, v158
	v_exp_f32_e32 v159, v159
	ds_read_b128 v[234:237], v222 offset:49152
	s_waitcnt lgkmcnt(2)
	v_mfma_f32_32x32x16_bf16 v[98:113], v[226:229], v[146:149], v[98:113]
	v_exp_f32_e32 v160, v160
	v_exp_f32_e32 v161, v161
	v_add_f32_e32 v254, v254, v154
	ds_read_b128 v[226:229], v222 offset:53248
	s_waitcnt lgkmcnt(2)
	v_mfma_f32_32x32x16_bf16 v[82:97], v[230:233], v[146:149], v[82:97]
	v_add_f32_e32 v255, v255, v155
	v_add_f32_e32 v254, v254, v156
	v_add_f32_e32 v255, v255, v157
	ds_read_b128 v[230:233], v222 offset:57344
	s_waitcnt lgkmcnt(2)
	v_mfma_f32_32x32x16_bf16 v[66:81], v[234:237], v[146:149], v[66:81]
	v_add_f32_e32 v254, v254, v158
	v_add_f32_e32 v255, v255, v159
	v_add_f32_e32 v254, v254, v160
	ds_read_b128 v[234:237], v222 offset:61440
	s_waitcnt lgkmcnt(2)
	v_mfma_f32_32x32x16_bf16 v[50:65], v[226:229], v[146:149], v[50:65]
	v_add_f32_e32 v255, v255, v161
	v_cvt_pk_bf16_f32 v154, v154, v155
	v_cvt_pk_bf16_f32 v155, v156, v157
	ds_read_b128 v[226:229], v223 offset:32768
	s_waitcnt lgkmcnt(2)
	v_mfma_f32_32x32x16_bf16 v[34:49], v[230:233], v[146:149], v[34:49]
	v_cvt_pk_bf16_f32 v156, v158, v159
	v_cvt_pk_bf16_f32 v157, v160, v161
	ds_read_b128 v[230:233], v223 offset:36864
	s_waitcnt lgkmcnt(2)
	v_mfma_f32_32x32x16_bf16 v[18:33], v[234:237], v[146:149], v[18:33]
	ds_read_b128 v[234:237], v223 offset:40960
	s_waitcnt lgkmcnt(2)
	v_mfma_f32_32x32x16_bf16 v[130:145], v[226:229], v[154:157], v[130:145]
	v_exp_f32_e32 v238, v238
	v_exp_f32_e32 v239, v239
	v_exp_f32_e32 v240, v240
	ds_read_b128 v[226:229], v223 offset:45056
	s_waitcnt lgkmcnt(2)
	v_mfma_f32_32x32x16_bf16 v[114:129], v[230:233], v[154:157], v[114:129]
	v_exp_f32_e32 v241, v241
	v_exp_f32_e32 v242, v242
	v_exp_f32_e32 v243, v243
	ds_read_b128 v[230:233], v223 offset:49152
	s_waitcnt lgkmcnt(2)
	v_mfma_f32_32x32x16_bf16 v[98:113], v[234:237], v[154:157], v[98:113]
	v_exp_f32_e32 v244, v244
	v_exp_f32_e32 v245, v245
	v_add_f32_e32 v254, v254, v238
	ds_read_b128 v[234:237], v223 offset:53248
	s_waitcnt lgkmcnt(2)
	v_mfma_f32_32x32x16_bf16 v[82:97], v[226:229], v[154:157], v[82:97]
	v_add_f32_e32 v255, v255, v239
	v_add_f32_e32 v254, v254, v240
	v_add_f32_e32 v255, v255, v241
	ds_read_b128 v[226:229], v223 offset:57344
	s_waitcnt lgkmcnt(2)
	v_mfma_f32_32x32x16_bf16 v[66:81], v[230:233], v[154:157], v[66:81]
	v_add_f32_e32 v254, v254, v242
	v_add_f32_e32 v255, v255, v243
	v_add_f32_e32 v254, v254, v244
	ds_read_b128 v[230:233], v223 offset:61440
	s_waitcnt lgkmcnt(2)
	v_mfma_f32_32x32x16_bf16 v[50:65], v[234:237], v[154:157], v[50:65]
	v_add_f32_e32 v255, v255, v245
	v_cvt_pk_bf16_f32 v238, v238, v239
	v_cvt_pk_bf16_f32 v239, v240, v241
	ds_read_b128 v[234:237], v224 offset:32768
	s_waitcnt lgkmcnt(2)
	v_mfma_f32_32x32x16_bf16 v[34:49], v[226:229], v[154:157], v[34:49]
	v_cvt_pk_bf16_f32 v240, v242, v243
	v_cvt_pk_bf16_f32 v241, v244, v245
	ds_read_b128 v[226:229], v224 offset:36864
	s_waitcnt lgkmcnt(2)
	v_mfma_f32_32x32x16_bf16 v[18:33], v[230:233], v[154:157], v[18:33]
	ds_read_b128 v[230:233], v224 offset:40960
	s_andn2_b64 vcc, exec, s[12:13]
	s_cbranch_vccnz .Lat_pv1
	s_mov_b32 s44, m0
	s_mov_b32 m0, s84
	s_nop 0
	global_load_lds_dwordx4 v206, s[0:1]
	s_mov_b32 m0, s44
	s_add_i32 s44, s84, 0x400
	s_mov_b32 s45, m0
	s_mov_b32 m0, s44
	s_nop 0
	global_load_lds_dwordx4 v208, s[0:1]
	s_mov_b32 m0, s45
	s_add_i32 s44, s84, 0x800
	s_mov_b32 s45, m0
	s_mov_b32 m0, s44
	s_nop 0
	global_load_lds_dwordx4 v209, s[0:1]
	s_mov_b32 m0, s45
	s_add_i32 s44, s84, 0xc00
	s_mov_b32 s45, m0
	s_mov_b32 m0, s44
	s_nop 0
	global_load_lds_dwordx4 v210, s[0:1]
	s_mov_b32 m0, s45
	s_mov_b32 s44, m0
	s_mov_b32 m0, s85
	s_nop 0
	global_load_lds_dwordx4 v207, s[42:43]
	s_mov_b32 m0, s44
	s_add_i32 s44, s85, 0x400
	s_mov_b32 s45, m0
	s_mov_b32 m0, s44
	s_nop 0
	global_load_lds_dwordx4 v211, s[42:43]
	s_mov_b32 m0, s45
	s_add_i32 s44, s85, 0x800
	s_mov_b32 s45, m0
	s_mov_b32 m0, s44
	s_nop 0
	global_load_lds_dwordx4 v212, s[42:43]
	s_mov_b32 m0, s45
	s_add_i32 s44, s85, 0xc00
	s_mov_b32 s45, m0
	s_mov_b32 m0, s44
	s_nop 0
	global_load_lds_dwordx4 v213, s[42:43]
	s_mov_b32 m0, s45
; #define LAS __attribute__((address_space(3)))
; __device__ __forceinline__ unsigned pk2(float lo, float hi) { return pg8::cvt_pk_bf16(lo, hi); }
; __device__ __forceinline__ void attn_block(LAS unsigned char* lds, const Ptrs& P, int b, int h, int qb, float negMb, float lam, int tid, int wid, int lane) {
;     ...
;                 for (int sI = 0; sI < 2; ++sI) { v4u w;
; #pragma unroll
;                     for (int j = 0; j < 4; ++j) w[j] = pk2(s[8 * sI + 2 * j], s[8 * sI + 2 * j + 1]);
;                     const bf16x8 pf = __builtin_bit_cast(bf16x8, w);
;                     const LAS unsigned char* vb = base + voffr + (((2 * (2 * T + sI) + hhb) ^ vx) << 4);
; #pragma unroll
;                     for (int e = 0; e < 8; ++e) {
;                         const bf16x8 vf = *(const LAS bf16x8*)(vb + e * 4096);
;                         o[e] = __builtin_amdgcn_mfma_f32_32x32x16_bf16(vf, pf, o[e], 0, 0, 0);
;                     }
;                 }
;             }
;         }
;     }
.Lat_pv1:
	s_waitcnt lgkmcnt(2)
	v_mfma_f32_32x32x16_bf16 v[130:145], v[234:237], v[238:241], v[130:145]
	v_exp_f32_e32 v246, v246
	v_exp_f32_e32 v247, v247
	v_exp_f32_e32 v248, v248
	ds_read_b128 v[234:237], v224 offset:45056
	s_waitcnt lgkmcnt(2)
	v_mfma_f32_32x32x16_bf16 v[114:129], v[226:229], v[238:241], v[114:129]
	v_exp_f32_e32 v249, v249
	v_exp_f32_e32 v250, v250
	v_exp_f32_e32 v251, v251
	ds_read_b128 v[226:229], v224 offset:49152
	s_waitcnt lgkmcnt(2)
	v_mfma_f32_32x32x16_bf16 v[98:113], v[230:233], v[238:241], v[98:113]
	v_exp_f32_e32 v252, v252
	v_exp_f32_e32 v253, v253
	v_add_f32_e32 v254, v254, v246
	ds_read_b128 v[230:233], v224 offset:53248
	s_waitcnt lgkmcnt(2)
	v_mfma_f32_32x32x16_bf16 v[82:97], v[234:237], v[238:241], v[82:97]
	v_add_f32_e32 v255, v255, v247
	v_add_f32_e32 v254, v254, v248
	v_add_f32_e32 v255, v255, v249
	ds_read_b128 v[234:237], v224 offset:57344
	s_waitcnt lgkmcnt(2)
	v_mfma_f32_32x32x16_bf16 v[66:81], v[226:229], v[238:241], v[66:81]
	v_add_f32_e32 v254, v254, v250
	v_add_f32_e32 v255, v255, v251
	v_add_f32_e32 v254, v254, v252
	ds_read_b128 v[226:229], v224 offset:61440
	s_waitcnt lgkmcnt(2)
	v_mfma_f32_32x32x16_bf16 v[50:65], v[230:233], v[238:241], v[50:65]
	v_add_f32_e32 v255, v255, v253
	v_cvt_pk_bf16_f32 v246, v246, v247
	v_cvt_pk_bf16_f32 v247, v248, v249
	ds_read_b128 v[230:233], v225 offset:32768
	s_waitcnt lgkmcnt(2)
	v_mfma_f32_32x32x16_bf16 v[34:49], v[234:237], v[238:241], v[34:49]
	v_cvt_pk_bf16_f32 v248, v250, v251
	v_cvt_pk_bf16_f32 v249, v252, v253
	ds_read_b128 v[234:237], v225 offset:36864
	s_waitcnt lgkmcnt(2)
	v_mfma_f32_32x32x16_bf16 v[18:33], v[226:229], v[238:241], v[18:33]
	ds_read_b128 v[226:229], v225 offset:40960
	s_waitcnt lgkmcnt(2)
	v_mfma_f32_32x32x16_bf16 v[130:145], v[230:233], v[246:249], v[130:145]
	v_xor_b32_e32 v214, 0x10000, v214
	v_xor_b32_e32 v215, 0x10000, v215
	ds_read_b128 v[230:233], v225 offset:45056
	s_waitcnt lgkmcnt(2)
	v_mfma_f32_32x32x16_bf16 v[114:129], v[234:237], v[246:249], v[114:129]
	v_xor_b32_e32 v216, 0x10000, v216
	v_xor_b32_e32 v217, 0x10000, v217
	ds_read_b128 v[234:237], v225 offset:49152
	s_waitcnt lgkmcnt(2)
	v_mfma_f32_32x32x16_bf16 v[98:113], v[226:229], v[246:249], v[98:113]
	v_xor_b32_e32 v218, 0x10000, v218
	v_xor_b32_e32 v219, 0x10000, v219
	ds_read_b128 v[242:245], v225 offset:53248
	ds_read_b128 v[250:253], v225 offset:57344
	ds_read_b128 v[238:241], v225 offset:61440
	s_waitcnt lgkmcnt(4)
	v_mfma_f32_32x32x16_bf16 v[82:97], v[230:233], v[246:249], v[82:97]
	v_xor_b32_e32 v220, 0x10000, v220
	v_xor_b32_e32 v221, 0x10000, v221
	s_waitcnt lgkmcnt(3)
	v_mfma_f32_32x32x16_bf16 v[66:81], v[234:237], v[246:249], v[66:81]
	v_xor_b32_e32 v222, 0x10000, v222
	v_xor_b32_e32 v223, 0x10000, v223
	s_waitcnt vmcnt(0)
	s_waitcnt lgkmcnt(0)
	s_barrier
	s_add_i32 s81, s81, 0x10000
	s_add_u32 s42, s42, 0x80
	s_addc_u32 s43, s43, 0
	s_add_u32 s0, s0, 0x20000
	s_addc_u32 s1, s1, 0
	ds_read_b128 v[226:229], v214
	ds_read_b128 v[230:233], v215
	ds_read_b128 v[234:237], v216
	v_mfma_f32_32x32x16_bf16 v[50:65], v[242:245], v[246:249], v[50:65]
	v_xor_b32_e32 v224, 0x10000, v224
	v_mfma_f32_32x32x16_bf16 v[34:49], v[250:253], v[246:249], v[34:49]
	v_xor_b32_e32 v225, 0x10000, v225
	v_mfma_f32_32x32x16_bf16 v[18:33], v[238:241], v[246:249], v[18:33]
	s_cmp_eq_u32 s82, s81
	s_cbranch_scc0 .Lat_tile
	s_not_b64 s[2:3], s[12:13]
	s_nop 0
	v_add_f32_e32 v194, v194, v254
	v_add_f32_e32 v194, v194, v255
